# attnB fast path v2: V frags pre-read before barrier, slim DMA head interleaved after M5-7, QK MFMAs paired on shared B operand
# baseline (speedup 1.0000x reference)
; #define B_BARRIER() { if (MODE != 4) { asm volatile("s_waitcnt vmcnt(0) lgkmcnt(0)" ::: "memory"); __builtin_amdgcn_s_barrier(); asm volatile("" ::: "memory"); } }
; template <int MODE>
; DI void attn_b_phase(unsigned char* ws, unsigned char* lds, int tid) {
;     ...
;         f32x16 S0[2], S1[2];
;         B_QK(S0, BK_OFF0);
;         B_BARRIER();
;         u32x4 pw[2][2];
; #pragma unroll
;         for (int sb = 0; sb < 2; ++sb)
; #pragma unroll
;             for (int s = 0; s < 2; ++s) pw[sb][s] = (u32x4){0u, 0u, 0u, 0u};
;         unsigned kcur = BK_OFF0, knext = KV_VOFF;
;         unsigned vprev = BV_OFF0 + 2 * BV_SZ, vcur = BV_OFF0, vnext = BV_OFF0 + BV_SZ;
.LBB0_1082:
	ds_read_b128 v[0:3], v161
	ds_read_b128 v[16:19], v161 offset:32
	s_mov_b32 s38, s37
	s_mov_b32 s39, s37
	s_mov_b32 s36, s37
	s_waitcnt vmcnt(0) lgkmcnt(0)
	v_mfma_f32_32x32x16_bf16 v[0:15], v[0:3], v[104:107], 0
	v_mov_b64_e32 v[66:67], s[38:39]
	v_mov_b64_e32 v[64:65], s[36:37]
	s_mov_b32 s40, s37
	s_mov_b32 s41, s37
	s_mov_b32 s42, s37
	s_mov_b32 s43, s37
	s_mov_b32 s44, s37
	v_mfma_f32_32x32x16_bf16 v[0:15], v[16:19], v[108:111], v[0:15]
	ds_read_b128 v[16:19], v161 offset:64
	ds_read_b128 v[20:23], v161 offset:96
	s_mov_b32 s45, s37
	s_mov_b32 s46, s37
	s_mov_b32 s47, s37
	s_mov_b32 s48, s37
	s_mov_b32 s49, s37
	s_mov_b32 s50, s37
	s_waitcnt lgkmcnt(1)
	v_mfma_f32_32x32x16_bf16 v[0:15], v[16:19], v[112:115], v[0:15]
	ds_read_b128 v[16:19], v161 offset:128
	s_mov_b32 s51, s37
	v_mov_b64_e32 v[32:33], s[36:37]
	s_mul_i32 s19, s34, 0x318000
	v_mov_b64_e32 v[34:35], s[38:39]
	v_mov_b64_e32 v[36:37], s[40:41]
	v_mov_b64_e32 v[38:39], s[42:43]
	s_waitcnt lgkmcnt(1)
	v_mfma_f32_32x32x16_bf16 v[0:15], v[20:23], v[116:119], v[0:15]
	ds_read_b128 v[20:23], v161 offset:160
	v_mov_b64_e32 v[40:41], s[44:45]
	v_mov_b64_e32 v[42:43], s[46:47]
	v_mov_b64_e32 v[44:45], s[48:49]
	v_mov_b64_e32 v[46:47], s[50:51]
	s_mul_hi_i32 s18, s34, 0x318000
	s_add_u32 s36, s27, s19
	s_waitcnt lgkmcnt(1)
	v_mfma_f32_32x32x16_bf16 v[0:15], v[16:19], v[120:123], v[0:15]
	ds_read_b128 v[16:19], v161 offset:7680
	ds_read_b128 v[48:51], v161 offset:7712
	ds_read_b128 v[52:55], v161 offset:7744
	s_addc_u32 s44, s33, s18
	s_add_u32 s38, s12, 0x12000
	v_mov_b32_e32 v96, 0
	v_ashrrev_i32_e32 v155, 31, v154
	s_addc_u32 s39, s13, 0
	s_waitcnt lgkmcnt(3)
	v_mfma_f32_32x32x16_bf16 v[0:15], v[20:23], v[124:127], v[0:15]
	s_mov_b32 s46, 0x9c00
	s_movk_i32 s45, 0x7800
	s_mov_b32 s12, 0xc000
	s_mov_b64 s[40:41], 0
	v_mov_b32_e32 v165, 0
	s_movk_i32 s47, 0xff7e
	v_mov_b32_e32 v151, 0
	s_waitcnt lgkmcnt(2)
	v_mfma_f32_32x32x16_bf16 v[16:31], v[16:19], v[104:107], 0
	v_mov_b32_e32 v140, v96
	v_mov_b32_e32 v141, v96
	v_mov_b32_e32 v142, v96
	v_mov_b32_e32 v143, v96
	v_mov_b32_e32 v136, v96
	v_mov_b32_e32 v137, v96
	v_mov_b32_e32 v138, v96
	s_waitcnt lgkmcnt(1)
	v_mfma_f32_32x32x16_bf16 v[16:31], v[48:51], v[108:111], v[16:31]
	ds_read_b128 v[48:51], v161 offset:7776
	ds_read_b128 v[68:71], v161 offset:7808
	ds_read_b128 v[72:75], v161 offset:7840
	s_waitcnt vmcnt(0) lgkmcnt(0)
	s_barrier
	v_mov_b32_e32 v139, v96
	v_mov_b32_e32 v132, v96
	v_mov_b32_e32 v133, v96
	s_waitcnt lgkmcnt(3)
	v_mfma_f32_32x32x16_bf16 v[16:31], v[52:55], v[112:115], v[16:31]
	v_mov_b32_e32 v134, v96
	v_mov_b32_e32 v135, v96
	v_mov_b32_e32 v128, v96
	v_mov_b32_e32 v129, v96
	v_mov_b32_e32 v130, v96
	v_mov_b32_e32 v131, v96
	s_waitcnt lgkmcnt(2)
	v_mfma_f32_32x32x16_bf16 v[16:31], v[48:51], v[116:119], v[16:31]
	v_mov_b64_e32 v[62:63], v[46:47]
	v_mov_b64_e32 v[60:61], v[44:45]
	v_mov_b64_e32 v[58:59], v[42:43]
	v_mov_b64_e32 v[56:57], v[40:41]
	v_mov_b64_e32 v[54:55], v[38:39]
	v_mov_b64_e32 v[52:53], v[36:37]
	v_mov_b64_e32 v[50:51], v[34:35]
	s_waitcnt lgkmcnt(1)
	v_mfma_f32_32x32x16_bf16 v[16:31], v[68:71], v[120:123], v[16:31]
	v_mov_b64_e32 v[48:49], v[32:33]
	s_waitcnt lgkmcnt(0)
	v_mfma_f32_32x32x16_bf16 v[16:31], v[72:75], v[124:127], v[16:31]
	v_mfma_f32_32x32x16_bf16 v[0:15], v[100:103], v[64:67], v[0:15]
	v_mfma_f32_32x32x16_bf16 v[16:31], v[100:103], v[64:67], v[16:31]
	s_mov_b32 s82, 0
.LBB0_1083:
	s_mov_b32 s48, s45
	s_mov_b32 s45, s12
	v_add_co_u32_e64 v164, s[12:13], s47, v162
	s_cmp_lg_u32 s82, 0
	s_cbranch_scc0 .Lold_it1
	s_waitcnt lgkmcnt(3)
	v_mfma_f32_32x32x16_bf16 v[48:63], v[184:187], v[128:131], v[48:63]
	s_add_u32 s84, s38, 0xffffa000
	s_addc_u32 s85, s39, -1
	s_add_u32 s86, s84, s58
	s_addc_u32 s87, s85, s59
	s_add_u32 s88, s84, s60
	s_addc_u32 s89, s85, s61
	s_add_u32 s90, s38, s52
	s_addc_u32 s91, s39, s53
	s_and_b64 s[18:19], s[10:11], exec
	s_cselect_b32 s88, s88, s90
	s_cselect_b32 s89, s89, s91
	s_cselect_b32 s18, s60, s46
	s_add_u32 s90, s38, s54
	s_addc_u32 s91, s39, s55
	s_add_i32 s34, s45, 16
	s_add_i32 s19, s74, s46
	s_xor_b64 s[42:43], s[40:41], -1
	v_lshl_add_u64 v[64:65], s[86:87], 0, v[144:145]
	v_lshl_add_u64 v[66:67], s[88:89], 0, v[144:145]
	v_lshl_add_u64 v[68:69], s[90:91], 0, v[152:153]
	ds_read_b128 v[216:219], v199 offset:64
	v_exp_f32_e32 v168, v0
	s_waitcnt lgkmcnt(3)
	v_mfma_f32_32x32x16_bf16 v[32:47], v[192:195], v[128:131], v[32:47]
	ds_read_b128 v[220:223], v199 offset:4672
	v_exp_f32_e32 v169, v1
	v_exp_f32_e32 v170, v2
	v_exp_f32_e32 v171, v3
	s_waitcnt lgkmcnt(3)
	v_mfma_f32_32x32x16_bf16 v[48:63], v[208:211], v[132:135], v[48:63]
	ds_read_b128 v[224:227], v199 offset:96
	v_exp_f32_e32 v172, v4
	v_exp_f32_e32 v173, v5
	v_add_f32_e32 v98, v169, v168
	v_cvt_pk_bf16_f32 v128, v168, v169
	s_waitcnt lgkmcnt(3)
	v_mfma_f32_32x32x16_bf16 v[32:47], v[212:215], v[132:135], v[32:47]
	ds_read_b128 v[228:231], v199 offset:4704
	v_exp_f32_e32 v174, v6
	v_exp_f32_e32 v175, v7
	v_add_f32_e32 v98, v170, v98
	v_add_f32_e32 v98, v171, v98
	v_cvt_pk_bf16_f32 v129, v170, v171
	s_waitcnt lgkmcnt(3)
	v_mfma_f32_32x32x16_bf16 v[48:63], v[216:219], v[136:139], v[48:63]
	ds_read_b128 v[232:235], v161 offset:15360
	v_exp_f32_e32 v176, v8
	v_exp_f32_e32 v177, v9
	v_add_f32_e32 v98, v172, v98
	v_add_f32_e32 v98, v173, v98
	s_waitcnt lgkmcnt(3)
	v_mfma_f32_32x32x16_bf16 v[32:47], v[220:223], v[136:139], v[32:47]
	s_mov_b32 m0, s74
	s_nop 0
	global_load_lds_dwordx4 v[64:65], off
	ds_read_b128 v[236:239], v161 offset:23040
	v_cvt_pk_bf16_f32 v130, v172, v173
	v_exp_f32_e32 v178, v10
	s_waitcnt lgkmcnt(3)
	v_mfma_f32_32x32x16_bf16 v[48:63], v[224:227], v[140:143], v[48:63]
	s_add_i32 m0, s18, 16
	s_nop 0
	global_load_lds_dwordx4 v[66:67], off
	ds_read_b128 v[240:243], v161 offset:15392
	v_exp_f32_e32 v179, v11
	v_add_f32_e32 v98, v174, v98
	v_add_f32_e32 v98, v175, v98
	v_cvt_pk_bf16_f32 v131, v174, v175
	s_waitcnt lgkmcnt(3)
	v_mfma_f32_32x32x16_bf16 v[32:47], v[228:231], v[140:143], v[32:47]
	s_add_i32 m0, s19, 0x400
	s_nop 0
	global_load_lds_dwordx4 v[68:69], off
	ds_read_b128 v[184:187], v161 offset:23072
	v_exp_f32_e32 v180, v12
	v_exp_f32_e32 v181, v13
	s_waitcnt lgkmcnt(3)
	v_mfma_f32_32x32x16_bf16 v[64:79], v[232:235], v[104:107], 0
	ds_read_b128 v[192:195], v161 offset:15424
	v_add_f32_e32 v98, v176, v98
	v_add_f32_e32 v98, v177, v98
	v_cvt_pk_bf16_f32 v132, v176, v177
	v_exp_f32_e32 v182, v14
	s_waitcnt lgkmcnt(3)
	v_mfma_f32_32x32x16_bf16 v[80:95], v[236:239], v[104:107], 0
	ds_read_b128 v[208:211], v161 offset:23104
	v_exp_f32_e32 v183, v15
	v_add_f32_e32 v98, v178, v98
	v_add_f32_e32 v98, v179, v98
	v_cvt_pk_bf16_f32 v133, v178, v179
	v_exp_f32_e32 v168, v16
	s_waitcnt lgkmcnt(3)
	v_mfma_f32_32x32x16_bf16 v[64:79], v[240:243], v[108:111], v[64:79]
	ds_read_b128 v[212:215], v161 offset:15456
	v_exp_f32_e32 v169, v17
	v_add_f32_e32 v98, v180, v98
	v_add_f32_e32 v98, v181, v98
	v_cvt_pk_bf16_f32 v134, v180, v181
	s_waitcnt lgkmcnt(3)
	v_mfma_f32_32x32x16_bf16 v[80:95], v[184:187], v[108:111], v[80:95]
	ds_read_b128 v[216:219], v161 offset:23136
	v_exp_f32_e32 v170, v18
	v_exp_f32_e32 v171, v19
	v_add_f32_e32 v98, v182, v98
	v_add_f32_e32 v98, v183, v98
	v_cvt_pk_bf16_f32 v135, v182, v183
	s_waitcnt lgkmcnt(3)
	v_mfma_f32_32x32x16_bf16 v[64:79], v[192:195], v[112:115], v[64:79]
	ds_read_b128 v[220:223], v161 offset:15488
	v_exp_f32_e32 v172, v20
	v_exp_f32_e32 v173, v21
	v_add_f32_e32 v98, v168, v98
	v_add_f32_e32 v98, v169, v98
	s_waitcnt lgkmcnt(3)
	v_mfma_f32_32x32x16_bf16 v[80:95], v[208:211], v[112:115], v[80:95]
	ds_read_b128 v[224:227], v161 offset:23168
	v_cvt_pk_bf16_f32 v136, v168, v169
	v_exp_f32_e32 v174, v22
	v_exp_f32_e32 v175, v23
	v_add_f32_e32 v98, v170, v98
	s_waitcnt lgkmcnt(3)
	v_mfma_f32_32x32x16_bf16 v[64:79], v[212:215], v[116:119], v[64:79]
	ds_read_b128 v[228:231], v161 offset:15520
	v_add_f32_e32 v98, v171, v98
	v_cvt_pk_bf16_f32 v137, v170, v171
	v_exp_f32_e32 v176, v24
	v_exp_f32_e32 v177, v25
	s_waitcnt lgkmcnt(3)
	v_mfma_f32_32x32x16_bf16 v[80:95], v[216:219], v[116:119], v[80:95]
	ds_read_b128 v[232:235], v161 offset:23200
	v_add_f32_e32 v98, v172, v98
	v_add_f32_e32 v98, v173, v98
	v_cvt_pk_bf16_f32 v138, v172, v173
	v_exp_f32_e32 v178, v26
	s_waitcnt lgkmcnt(3)
	v_mfma_f32_32x32x16_bf16 v[64:79], v[220:223], v[120:123], v[64:79]
	v_exp_f32_e32 v179, v27
	v_add_f32_e32 v98, v174, v98
	v_add_f32_e32 v98, v175, v98
	v_cvt_pk_bf16_f32 v139, v174, v175
	v_exp_f32_e32 v180, v28
	s_waitcnt lgkmcnt(2)
	v_mfma_f32_32x32x16_bf16 v[80:95], v[224:227], v[120:123], v[80:95]
	v_exp_f32_e32 v181, v29
	v_add_f32_e32 v98, v176, v98
	v_add_f32_e32 v98, v177, v98
	v_cvt_pk_bf16_f32 v140, v176, v177
	s_waitcnt lgkmcnt(1)
	v_mfma_f32_32x32x16_bf16 v[64:79], v[228:231], v[124:127], v[64:79]
	v_exp_f32_e32 v182, v30
	v_exp_f32_e32 v183, v31
	v_add_f32_e32 v98, v178, v98
	v_add_f32_e32 v98, v179, v98
	v_cvt_pk_bf16_f32 v141, v178, v179
	s_waitcnt lgkmcnt(0)
	v_mfma_f32_32x32x16_bf16 v[80:95], v[232:235], v[124:127], v[80:95]
	v_add_f32_e32 v98, v180, v98
	v_add_f32_e32 v98, v181, v98
	v_cvt_pk_bf16_f32 v142, v180, v181
	v_add_f32_e32 v98, v182, v98
	v_add_f32_e32 v167, v183, v98
	v_cvt_pk_bf16_f32 v143, v182, v183
	s_branch .LBB0_1094
.Lold_it1:
	s_andn2_b64 vcc, exec, s[12:13]
	s_mov_b64 s[34:35], -1
	s_cbranch_vccz .LBB0_1085
	s_mul_i32 s18, s47, 0x6000
	s_mul_hi_u32 s19, s47, 0x6000
	s_add_u32 s18, s36, s18
	s_addc_u32 s19, s44, s19
	s_mov_b64 s[34:35], 0

.LBB0_1087:
	v_lshl_add_u64 v[64:65], s[18:19], 0, v[144:145]
	v_lshl_add_u64 v[68:69], s[38:39], 0, v[144:145]
	s_and_b64 s[18:19], s[10:11], exec
	s_mov_b32 m0, s74
	v_lshl_add_u64 v[66:67], v[64:65], 0, s[60:61]
	v_lshl_add_u64 v[68:69], v[68:69], 0, s[52:53]
	s_cselect_b32 s18, s60, s46
	v_lshl_add_u64 v[64:65], v[64:65], 0, s[58:59]
	v_cndmask_b32_e64 v67, v69, v67, s[10:11]
	v_cndmask_b32_e64 v66, v68, v66, s[10:11]
	global_load_lds_dwordx4 v[64:65], off
	s_add_i32 m0, s18, 16
	v_lshl_add_u64 v[64:65], s[38:39], 0, v[152:153]
	s_add_i32 s18, s74, s46
	global_load_lds_dwordx4 v[66:67], off
	v_lshl_add_u64 v[64:65], v[64:65], 0, s[54:55]
	s_add_i32 m0, s18, 0x400
	s_add_i32 s34, s45, 16
	global_load_lds_dwordx4 v[64:65], off
	v_add_u32_e32 v76, s34, v157
	ds_read_b128 v[64:67], v76
	ds_read_b128 v[68:71], v76 offset:32
	s_waitcnt lgkmcnt(0)
	v_mfma_f32_32x32x16_bf16 v[48:63], v[64:67], v[128:131], v[48:63]
	ds_read_b128 v[64:67], v76 offset:4608
	ds_read_b128 v[72:75], v76 offset:4640
	s_cmpk_lg_i32 s47, 0xff7e
	s_waitcnt lgkmcnt(0)
	v_mfma_f32_32x32x16_bf16 v[32:47], v[64:67], v[128:131], v[32:47]
	v_mfma_f32_32x32x16_bf16 v[48:63], v[68:71], v[132:135], v[48:63]
	ds_read_b128 v[64:67], v76 offset:64
	ds_read_b128 v[68:71], v76 offset:96
	v_mfma_f32_32x32x16_bf16 v[32:47], v[72:75], v[132:135], v[32:47]
	s_waitcnt lgkmcnt(0)
	v_mfma_f32_32x32x16_bf16 v[48:63], v[64:67], v[136:139], v[48:63]
	ds_read_b128 v[64:67], v76 offset:4672
	ds_read_b128 v[72:75], v76 offset:4704
	s_waitcnt lgkmcnt(0)
	v_mfma_f32_32x32x16_bf16 v[32:47], v[64:67], v[136:139], v[32:47]
	v_mfma_f32_32x32x16_bf16 v[48:63], v[68:71], v[140:143], v[48:63]
	v_mfma_f32_32x32x16_bf16 v[32:47], v[72:75], v[140:143], v[32:47]
	s_cbranch_scc1 .LBB0_1092
	v_max_f32_e32 v64, v1, v1
	v_max_f32_e32 v65, v0, v0
	v_max_f32_e32 v64, v65, v64
	v_max3_f32 v64, v64, v2, v3
	v_max3_f32 v64, v64, v4, v5
	v_max3_f32 v64, v64, v6, v7
	v_max3_f32 v64, v64, v8, v9
	v_max3_f32 v64, v64, v10, v11
	v_max3_f32 v64, v64, v12, v13
	v_max3_f32 v64, v64, v14, v15
	v_max3_f32 v64, v64, v16, v17
	v_max3_f32 v64, v64, v18, v19
	v_max3_f32 v64, v64, v20, v21
	v_max3_f32 v64, v64, v22, v23
	v_and_b32_e32 v66, 64, v163
	v_max3_f32 v64, v64, v24, v25
	v_xor_b32_e32 v65, 32, v163
	v_add_u32_e32 v66, 64, v66
	v_max3_f32 v64, v64, v26, v27
	v_cmp_lt_i32_e32 vcc, v65, v66
	v_max3_f32 v64, v64, v28, v29
	v_max3_f32 v64, v64, v30, v31
	v_cndmask_b32_e32 v65, v163, v65, vcc
	v_lshlrev_b32_e32 v65, 2, v65
	ds_bpermute_b32 v65, v65, v64
	s_waitcnt lgkmcnt(0)
	v_max_f32_e32 v65, v65, v65
	v_max_f32_e32 v64, v64, v65
	v_cmp_gt_f32_e64 vcc, |v64|, s70
	s_cbranch_vccz .LBB0_1092
	v_add_f32_e32 v64, v165, v64
	v_cvt_pk_bf16_f32 v64, v64, 0
	s_xor_b64 s[18:19], s[40:41], -1
	v_lshlrev_b32_e32 v64, 16, v64
	s_andn2_b64 vcc, exec, s[18:19]
	s_mov_b64 s[40:41], -1
	s_cbranch_vccnz .LBB0_1091
	v_cmp_neq_f32_e32 vcc, 0, v64
	s_cmp_lg_u64 vcc, 0
	s_cselect_b64 s[40:41], -1, 0

.LBB0_1101:
	s_cmp_lt_i32 s47, -1
	s_cselect_b32 s82, 1, 0
	s_cmp_eq_u64 s[40:41], 0
	s_cselect_b32 s83, 1, 0
	s_and_b32 s82, s82, s83
	v_add_u32_e32 v199, s48, v158
	ds_read_b128 v[184:187], v199
	ds_read_b128 v[192:195], v199 offset:4608
	ds_read_b128 v[208:211], v199 offset:32
	ds_read_b128 v[212:215], v199 offset:4640
	s_waitcnt vmcnt(0)
	s_barrier
	s_cmp_lg_u32 s82, 0
	s_cbranch_scc0 .Lold_it2
	s_waitcnt lgkmcnt(3)
	v_mfma_f32_32x32x16_bf16 v[48:63], v[184:187], v[128:131], v[48:63]
	s_add_u32 s84, s38, 0xffffa000
	s_addc_u32 s85, s39, -1
	s_add_u32 s86, s38, s58
	s_addc_u32 s87, s39, s59
	s_add_u32 s88, s38, s60
	s_addc_u32 s89, s39, s61
	s_add_u32 s90, s84, s56
	s_addc_u32 s91, s85, s57
	s_and_b64 s[12:13], s[10:11], exec
	s_cselect_b32 s88, s88, s90
	s_cselect_b32 s89, s89, s91
	s_cselect_b32 s12, s75, s45
	s_add_u32 s90, s84, s62
	s_addc_u32 s91, s85, s63
	s_add_i32 s13, s34, s58
	s_xor_b64 s[42:43], s[40:41], -1
	v_lshl_add_u64 v[0:1], s[86:87], 0, v[144:145]
	v_lshl_add_u64 v[2:3], s[88:89], 0, v[144:145]
	v_lshl_add_u64 v[4:5], s[90:91], 0, v[144:145]
	ds_read_b128 v[216:219], v199 offset:64
	v_exp_f32_e32 v168, v64
	s_waitcnt lgkmcnt(3)
	v_mfma_f32_32x32x16_bf16 v[32:47], v[192:195], v[128:131], v[32:47]
	ds_read_b128 v[220:223], v199 offset:4672
	v_exp_f32_e32 v169, v65
	v_exp_f32_e32 v170, v66
	v_exp_f32_e32 v171, v67
	s_waitcnt lgkmcnt(3)
	v_mfma_f32_32x32x16_bf16 v[48:63], v[208:211], v[132:135], v[48:63]
	ds_read_b128 v[224:227], v199 offset:96
	v_exp_f32_e32 v172, v68
	v_exp_f32_e32 v173, v69
	v_add_f32_e32 v98, v169, v168
	v_cvt_pk_bf16_f32 v128, v168, v169
	s_waitcnt lgkmcnt(3)
	v_mfma_f32_32x32x16_bf16 v[32:47], v[212:215], v[132:135], v[32:47]
	ds_read_b128 v[228:231], v199 offset:4704
	v_exp_f32_e32 v174, v70
	v_exp_f32_e32 v175, v71
	v_add_f32_e32 v98, v170, v98
	v_add_f32_e32 v98, v171, v98
	v_cvt_pk_bf16_f32 v129, v170, v171
	s_waitcnt lgkmcnt(3)
	v_mfma_f32_32x32x16_bf16 v[48:63], v[216:219], v[136:139], v[48:63]
	ds_read_b128 v[232:235], v161
	v_exp_f32_e32 v176, v72
	v_exp_f32_e32 v177, v73
	v_add_f32_e32 v98, v172, v98
	v_add_f32_e32 v98, v173, v98
	s_waitcnt lgkmcnt(3)
	v_mfma_f32_32x32x16_bf16 v[32:47], v[220:223], v[136:139], v[32:47]
	s_add_i32 m0, s74, 0x3c00
	s_nop 0
	global_load_lds_dwordx4 v[0:1], off
	ds_read_b128 v[236:239], v161 offset:7680
	v_cvt_pk_bf16_f32 v130, v172, v173
	v_exp_f32_e32 v178, v74
	s_waitcnt lgkmcnt(3)
	v_mfma_f32_32x32x16_bf16 v[48:63], v[224:227], v[140:143], v[48:63]
	s_add_i32 m0, s12, 16
	s_nop 0
	global_load_lds_dwordx4 v[2:3], off
	ds_read_b128 v[240:243], v161 offset:32
	v_exp_f32_e32 v179, v75
	v_add_f32_e32 v98, v174, v98
	v_add_f32_e32 v98, v175, v98
	v_cvt_pk_bf16_f32 v131, v174, v175
	s_waitcnt lgkmcnt(3)
	v_mfma_f32_32x32x16_bf16 v[32:47], v[228:231], v[140:143], v[32:47]
	s_add_i32 m0, s13, 0x400
	s_nop 0
	global_load_lds_dwordx4 v[4:5], off
	ds_read_b128 v[184:187], v161 offset:7712
	v_exp_f32_e32 v180, v76
	v_exp_f32_e32 v181, v77
	s_waitcnt lgkmcnt(3)
	v_mfma_f32_32x32x16_bf16 v[0:15], v[232:235], v[104:107], 0
	ds_read_b128 v[192:195], v161 offset:64
	v_add_f32_e32 v98, v176, v98
	v_add_f32_e32 v98, v177, v98
	v_cvt_pk_bf16_f32 v132, v176, v177
	v_exp_f32_e32 v182, v78
	s_waitcnt lgkmcnt(3)
	v_mfma_f32_32x32x16_bf16 v[16:31], v[236:239], v[104:107], 0
	ds_read_b128 v[208:211], v161 offset:7744
	v_exp_f32_e32 v183, v79
	v_add_f32_e32 v98, v178, v98
	v_add_f32_e32 v98, v179, v98
	v_cvt_pk_bf16_f32 v133, v178, v179
	v_exp_f32_e32 v168, v80
	s_waitcnt lgkmcnt(3)
	v_mfma_f32_32x32x16_bf16 v[0:15], v[240:243], v[108:111], v[0:15]
	ds_read_b128 v[212:215], v161 offset:96
	v_exp_f32_e32 v169, v81
	v_add_f32_e32 v98, v180, v98
	v_add_f32_e32 v98, v181, v98
	v_cvt_pk_bf16_f32 v134, v180, v181
	s_waitcnt lgkmcnt(3)
	v_mfma_f32_32x32x16_bf16 v[16:31], v[184:187], v[108:111], v[16:31]
	ds_read_b128 v[216:219], v161 offset:7776
	v_exp_f32_e32 v170, v82
	v_exp_f32_e32 v171, v83
	v_add_f32_e32 v98, v182, v98
	v_add_f32_e32 v98, v183, v98
	v_cvt_pk_bf16_f32 v135, v182, v183
	s_waitcnt lgkmcnt(3)
	v_mfma_f32_32x32x16_bf16 v[0:15], v[192:195], v[112:115], v[0:15]
	ds_read_b128 v[220:223], v161 offset:128
	v_exp_f32_e32 v172, v84
	v_exp_f32_e32 v173, v85
	v_add_f32_e32 v98, v168, v98
	v_add_f32_e32 v98, v169, v98
	s_waitcnt lgkmcnt(3)
	v_mfma_f32_32x32x16_bf16 v[16:31], v[208:211], v[112:115], v[16:31]
	ds_read_b128 v[224:227], v161 offset:7808
	v_cvt_pk_bf16_f32 v136, v168, v169
	v_exp_f32_e32 v174, v86
	v_exp_f32_e32 v175, v87
	v_add_f32_e32 v98, v170, v98
	s_waitcnt lgkmcnt(3)
	v_mfma_f32_32x32x16_bf16 v[0:15], v[212:215], v[116:119], v[0:15]
	ds_read_b128 v[228:231], v161 offset:160
	v_add_f32_e32 v98, v171, v98
	v_cvt_pk_bf16_f32 v137, v170, v171
	v_exp_f32_e32 v176, v88
	v_exp_f32_e32 v177, v89
	s_waitcnt lgkmcnt(3)
	v_mfma_f32_32x32x16_bf16 v[16:31], v[216:219], v[116:119], v[16:31]
	ds_read_b128 v[232:235], v161 offset:7840
	v_add_f32_e32 v98, v172, v98
	v_add_f32_e32 v98, v173, v98
	v_cvt_pk_bf16_f32 v138, v172, v173
	v_exp_f32_e32 v178, v90
	s_waitcnt lgkmcnt(3)
	v_mfma_f32_32x32x16_bf16 v[0:15], v[220:223], v[120:123], v[0:15]
	v_exp_f32_e32 v179, v91
	v_add_f32_e32 v98, v174, v98
	v_add_f32_e32 v98, v175, v98
	v_cvt_pk_bf16_f32 v139, v174, v175
	v_exp_f32_e32 v180, v92
	s_waitcnt lgkmcnt(2)
	v_mfma_f32_32x32x16_bf16 v[16:31], v[224:227], v[120:123], v[16:31]
	v_exp_f32_e32 v181, v93
	v_add_f32_e32 v98, v176, v98
	v_add_f32_e32 v98, v177, v98
	v_cvt_pk_bf16_f32 v140, v176, v177
	s_waitcnt lgkmcnt(1)
	v_mfma_f32_32x32x16_bf16 v[0:15], v[228:231], v[124:127], v[0:15]
	v_exp_f32_e32 v182, v94
	v_exp_f32_e32 v183, v95
	v_add_f32_e32 v98, v178, v98
	v_add_f32_e32 v98, v179, v98
	v_cvt_pk_bf16_f32 v141, v178, v179
	s_waitcnt lgkmcnt(0)
	v_mfma_f32_32x32x16_bf16 v[16:31], v[232:235], v[124:127], v[16:31]
	v_add_f32_e32 v98, v180, v98
	v_add_f32_e32 v98, v181, v98
	v_cvt_pk_bf16_f32 v142, v180, v181
	v_add_f32_e32 v98, v182, v98
	v_add_f32_e32 v190, v183, v98
	v_cvt_pk_bf16_f32 v143, v182, v183
	s_branch .LBB0_1105
.Lold_it2:
	v_cmp_gt_u32_e32 vcc, s72, v164
	s_xor_b64 s[42:43], s[40:41], -1
	s_mov_b64 s[18:19], s[38:39]
	s_cbranch_vccnz .LBB0_1103
	s_add_i32 s18, s47, 1
	s_mul_hi_u32 s19, s18, 0x6000
	s_mulk_i32 s18, 0x6000
	s_add_u32 s18, s36, s18
	s_addc_u32 s19, s44, s19
.LBB0_1103:
	s_add_u32 s35, s38, 0xffffa000
	s_addc_u32 s49, s39, -1
	s_and_b64 s[12:13], s[12:13], exec
	s_cselect_b32 s13, s49, s44
	s_cselect_b32 s12, s35, s36
	v_lshl_add_u64 v[0:1], s[18:19], 0, v[144:145]
	v_lshl_add_u64 v[2:3], s[12:13], 0, v[144:145]
	s_and_b64 s[12:13], s[10:11], exec
	v_lshl_add_u64 v[4:5], v[0:1], 0, s[60:61]
	v_lshl_add_u64 v[6:7], v[2:3], 0, s[56:57]
	s_cselect_b32 s12, s75, s45
	v_lshl_add_u64 v[0:1], v[0:1], 0, s[58:59]
	s_add_i32 m0, s74, 0x3c00
	v_cndmask_b32_e64 v5, v7, v5, s[10:11]
	v_cndmask_b32_e64 v4, v6, v4, s[10:11]
	global_load_lds_dwordx4 v[0:1], off
	s_add_i32 m0, s12, 16
	s_add_i32 s12, s34, s58
	global_load_lds_dwordx4 v[4:5], off
	v_lshl_add_u64 v[0:1], v[2:3], 0, s[62:63]
	s_add_i32 m0, s12, 0x400
	v_add_u32_e32 v12, s48, v158
	global_load_lds_dwordx4 v[0:1], off
	ds_read_b128 v[0:3], v12
	ds_read_b128 v[4:7], v12 offset:32
	s_waitcnt lgkmcnt(0)
	v_mfma_f32_32x32x16_bf16 v[48:63], v[0:3], v[128:131], v[48:63]
	ds_read_b128 v[0:3], v12 offset:4608
	ds_read_b128 v[8:11], v12 offset:4640
	v_exp_f32_e32 v196, v64
	v_exp_f32_e32 v198, v65
	v_exp_f32_e32 v195, v66
	v_exp_f32_e32 v197, v67
	v_exp_f32_e32 v192, v68
	v_exp_f32_e32 v194, v69
	s_waitcnt lgkmcnt(0)
	v_mfma_f32_32x32x16_bf16 v[32:47], v[0:3], v[128:131], v[32:47]
	v_exp_f32_e32 v191, v70
	v_exp_f32_e32 v193, v71
	v_exp_f32_e32 v188, v72
	v_exp_f32_e32 v189, v73
	v_exp_f32_e32 v186, v74
	v_exp_f32_e32 v187, v75
	v_exp_f32_e32 v184, v76
	v_mfma_f32_32x32x16_bf16 v[48:63], v[4:7], v[132:135], v[48:63]
	v_exp_f32_e32 v185, v77
	v_exp_f32_e32 v182, v78
	v_exp_f32_e32 v183, v79
	v_exp_f32_e32 v181, v80
	v_exp_f32_e32 v180, v81
	v_exp_f32_e32 v178, v82
	v_exp_f32_e32 v179, v83
	v_mfma_f32_32x32x16_bf16 v[32:47], v[8:11], v[132:135], v[32:47]
	ds_read_b128 v[0:3], v12 offset:64
	ds_read_b128 v[4:7], v12 offset:96
	ds_read_b128 v[8:11], v12 offset:4672
	ds_read_b128 v[12:15], v12 offset:4704
	v_exp_f32_e32 v176, v84
	v_exp_f32_e32 v177, v85
	v_exp_f32_e32 v174, v86
	v_exp_f32_e32 v175, v87
	v_exp_f32_e32 v172, v88
	v_exp_f32_e32 v173, v89
	s_waitcnt lgkmcnt(0)
	v_mfma_f32_32x32x16_bf16 v[48:63], v[0:3], v[136:139], v[48:63]
	v_exp_f32_e32 v170, v90
	v_exp_f32_e32 v171, v91
	v_exp_f32_e32 v168, v92
	v_exp_f32_e32 v169, v93
	v_exp_f32_e32 v164, v94
	v_exp_f32_e32 v165, v95
	s_mov_b64 s[12:13], -1
	v_mfma_f32_32x32x16_bf16 v[32:47], v[8:11], v[136:139], v[32:47]
	s_and_b64 vcc, exec, s[42:43]
	v_mfma_f32_32x32x16_bf16 v[48:63], v[4:7], v[140:143], v[48:63]
	v_mfma_f32_32x32x16_bf16 v[32:47], v[12:15], v[140:143], v[32:47]
	s_cbranch_vccz .LBB0_1109
	ds_read_b128 v[0:3], v161
	ds_read_b128 v[16:19], v161 offset:32
	ds_read_b128 v[20:23], v161 offset:64
	ds_read_b128 v[24:27], v161 offset:96
	v_add_f32_e32 v28, 0, v196
	v_add_f32_e32 v28, v198, v28
	s_waitcnt lgkmcnt(0)
	v_mfma_f32_32x32x16_bf16 v[0:15], v[0:3], v[104:107], 0
	v_cvt_pk_bf16_f32 v128, v196, v198
	v_add_f32_e32 v28, v195, v28
	v_cvt_pk_bf16_f32 v129, v195, v197
	v_add_f32_e32 v98, v197, v28
	v_mfma_f32_32x32x16_bf16 v[0:15], v[16:19], v[108:111], v[0:15]
	ds_read_b128 v[28:31], v161 offset:128
	v_add_f32_e32 v98, v192, v98
	v_add_f32_e32 v98, v194, v98
	v_cvt_pk_bf16_f32 v130, v192, v194
	v_add_f32_e32 v98, v191, v98
	v_cvt_pk_bf16_f32 v131, v191, v193
	v_add_f32_e32 v98, v193, v98
	v_mfma_f32_32x32x16_bf16 v[0:15], v[20:23], v[112:115], v[0:15]
	ds_read_b128 v[16:19], v161 offset:160
	v_add_f32_e32 v98, v188, v98
	v_add_f32_e32 v98, v189, v98
	v_cvt_pk_bf16_f32 v132, v188, v189
	v_add_f32_e32 v98, v186, v98
	v_cvt_pk_bf16_f32 v133, v186, v187
	v_add_f32_e32 v98, v187, v98
	v_mfma_f32_32x32x16_bf16 v[0:15], v[24:27], v[116:119], v[0:15]
	ds_read_b128 v[20:23], v161 offset:7680
	v_add_f32_e32 v98, v184, v98
	v_add_f32_e32 v98, v185, v98
	v_cvt_pk_bf16_f32 v134, v184, v185
	v_add_f32_e32 v98, v182, v98
	v_cvt_pk_bf16_f32 v135, v182, v183
	v_add_f32_e32 v98, v183, v98
	s_waitcnt lgkmcnt(0)
	v_mfma_f32_32x32x16_bf16 v[0:15], v[28:31], v[120:123], v[0:15]
	ds_read_b128 v[140:143], v161 offset:7712
	v_add_f32_e32 v24, v181, v98
	v_add_f32_e32 v24, v180, v24
	v_cvt_pk_bf16_f32 v136, v181, v180
	v_mfma_f32_32x32x16_bf16 v[0:15], v[16:19], v[124:127], v[0:15]
	ds_read_b128 v[208:211], v161 offset:7744
	v_add_f32_e32 v24, v178, v24
	v_cvt_pk_bf16_f32 v137, v178, v179
	v_add_f32_e32 v16, v179, v24
	v_add_f32_e32 v16, v176, v16
	v_add_f32_e32 v98, v177, v16
	v_mfma_f32_32x32x16_bf16 v[16:31], v[20:23], v[104:107], 0
	ds_read_b128 v[212:215], v161 offset:7776
	v_cvt_pk_bf16_f32 v138, v176, v177
	s_waitcnt lgkmcnt(0)
	v_mfma_f32_32x32x16_bf16 v[16:31], v[140:143], v[108:111], v[16:31]
	ds_read_b128 v[216:219], v161 offset:7808
	v_add_f32_e32 v98, v174, v98
	v_cvt_pk_bf16_f32 v139, v174, v175
	v_add_f32_e32 v98, v175, v98
	v_mfma_f32_32x32x16_bf16 v[16:31], v[208:211], v[112:115], v[16:31]
	ds_read_b128 v[220:223], v161 offset:7840
	v_add_f32_e32 v98, v172, v98
	v_cvt_pk_bf16_f32 v140, v172, v173
	v_add_f32_e32 v98, v173, v98
	v_mfma_f32_32x32x16_bf16 v[16:31], v[212:215], v[116:119], v[16:31]
	v_add_f32_e32 v98, v170, v98
	v_cvt_pk_bf16_f32 v141, v170, v171
	v_add_f32_e32 v98, v171, v98
	s_waitcnt lgkmcnt(0)
	v_mfma_f32_32x32x16_bf16 v[16:31], v[216:219], v[120:123], v[16:31]
	v_add_f32_e32 v98, v168, v98
	v_cvt_pk_bf16_f32 v142, v168, v169
	v_add_f32_e32 v98, v169, v98
	v_mfma_f32_32x32x16_bf16 v[16:31], v[220:223], v[124:127], v[16:31]
	v_add_f32_e32 v98, v164, v98
	v_add_f32_e32 v190, v165, v98
	v_cvt_pk_bf16_f32 v143, v164, v165
	s_cbranch_execz .LBB0_1110

; template <int MODE>
; DI void attn_b_phase(unsigned char* ws, unsigned char* lds, int tid) {
;     ...
;         for (int kt = 0; kt < KV_NT; kt += 2) {
;             B_ITER(S0, S1, kt)
;             B_ITER(S1, S0, kt + 1)
;         }
.LBB0_1112:
	s_add_i32 s12, s47, 2
	s_cmp_lt_i32 s12, -1
	s_cselect_b32 s82, 1, 0
	s_cmp_eq_u64 s[40:41], 0
	s_cselect_b32 s83, 1, 0
	s_and_b32 s82, s82, s83
	v_add_u32_e32 v199, s46, v158
	ds_read_b128 v[184:187], v199
	ds_read_b128 v[192:195], v199 offset:4608
	ds_read_b128 v[208:211], v199 offset:32
	ds_read_b128 v[212:215], v199 offset:4640
	s_waitcnt vmcnt(0)
	s_barrier
	s_add_u32 s38, s38, 0xc000
	s_addc_u32 s39, s39, 0
	s_add_i32 s13, s47, 0x82
	v_add_f32_e32 v151, v190, v98
	s_cmpk_gt_u32 s13, 0x81
	s_cbranch_scc1 .LBB0_1072
	s_mov_b32 s47, s12
	s_mov_b32 s12, s46
	s_mov_b32 s46, s48
	s_branch .LBB0_1083
